# v5: P6 second-row scale/shift parameters reused from the first row when same batch (uniform runtime check, reload fallback), on top of v4
# baseline (speedup 1.0000x reference)
; __device__ __forceinline__ unsigned pk2(float lo, float hi) { f32x2 v = {lo, hi}; bf16x2_t b = __builtin_convertvector(v, bf16x2_t); return __builtin_bit_cast(unsigned, b); }
; __device__ __forceinline__ float bf_lo(unsigned u) { return __uint_as_float(u << 16); }
; __device__ __forceinline__ float bf_hi(unsigned u) { return __uint_as_float(u & 0xffff0000u); }
; __device__ __forceinline__ void norm_rows_bf(const bf16_t* __restrict__ X, const float* __restrict__ g, const float* __restrict__ mod, int sh_off, int sc_off, bf16_t* __restrict__ H, int G) {
;     ...
; #pragma unroll
;         for (int q = 0; q < 2; ++q) { const int rq = (row0 + q * NGW < MTOK) ? row0 + q * NGW : row0; const u32x4* xr = (const u32x4*)(X + (size_t)rq * DM + 16 * lane);
;             w[q][0] = xr[0]; w[q][1] = xr[1]; }
; #pragma unroll
;         for (int q = 0; q < 2; ++q) { const int row = (row0 + q * NGW < MTOK) ? row0 + q * NGW : row0; const int b = row >> 12;
;             float v[16];
; #pragma unroll
;             for (int e = 0; e < 2; ++e) { v[8 * e] = bf_lo(w[q][e].x); v[8 * e + 1] = bf_hi(w[q][e].x); v[8 * e + 2] = bf_lo(w[q][e].y); v[8 * e + 3] = bf_hi(w[q][e].y);
;                 v[8 * e + 4] = bf_lo(w[q][e].z); v[8 * e + 5] = bf_hi(w[q][e].z); v[8 * e + 6] = bf_lo(w[q][e].w); v[8 * e + 7] = bf_hi(w[q][e].w); }
; #pragma unroll
;             for (int i = 0; i < 16; ++i) ss[q] += v[i] * v[i];
;             const float rn = __builtin_amdgcn_rsqf(wave_sum(ss[q]) * (1.0f / DM) + EPS);
;             const float* mb = mod + (size_t)b * NMOD; const int c = 16 * lane;
;             unsigned o[8];
; #pragma unroll
;             for (int j = 0; j < 4; ++j) { const f32x4 gv = *(const f32x4*)(g + c + 4 * j), sc = *(const f32x4*)(mb + sc_off + c + 4 * j), sh = *(const f32x4*)(mb + sh_off + c + 4 * j);
;                 const f32x4 x = (f32x4){v[4 * j], v[4 * j + 1], v[4 * j + 2], v[4 * j + 3]};
;                 const f32x4 y = x * rn * gv * (sc + 1.0f) + sh; o[2 * j] = pk2(y[0], y[1]); o[2 * j + 1] = pk2(y[2], y[3]); }
;             u32x4* op = (u32x4*)(H + (size_t)row * DM + c);
;             op[0] = (u32x4){o[0], o[1], o[2], o[3]}; op[1] = (u32x4){o[4], o[5], o[6], o[7]}; }
.LBB0_617:
	v_ashrrev_i32_e32 v17, 31, v16
	v_lshlrev_b64 v[64:65], 11, v[16:17]
	v_lshl_add_u64 v[18:19], v[22:23], 0, v[64:65]
	v_ashrrev_i32_e32 v17, 12, v16
	v_mov_b32_e32 v160, v17
	v_mul_hi_i32_i24_e32 v19, 0x6000, v17
	v_mul_i32_i24_e32 v18, 0x6000, v17
	v_lshl_add_u64 v[18:19], s[66:67], 0, v[18:19]
	v_lshl_add_u64 v[66:67], v[18:19], 0, v[20:21]
	v_add_co_u32_e32 v18, vcc, s12, v66
	v_add_u32_e32 v35, s3, v16
	s_nop 0
	v_addc_co_u32_e32 v19, vcc, 0, v67, vcc
	v_cmp_gt_i32_e32 vcc, s2, v35
	global_load_dwordx4 v[44:47], v[18:19], off
	v_lshl_add_u64 v[18:19], v[66:67], 0, s[8:9]
	v_cndmask_b32_e32 v80, v16, v35, vcc
	v_ashrrev_i32_e32 v81, 31, v80
	v_lshlrev_b64 v[26:27], 11, v[80:81]
	v_lshl_add_u64 v[68:69], v[22:23], 0, v[26:27]
	global_load_dwordx4 v[48:51], v[18:19], off offset:32
	global_load_dwordx4 v[52:55], v[18:19], off offset:16
	global_load_dwordx4 v[56:59], v[18:19], off offset:48
	s_nop 0
	v_add_co_u32_e32 v86, vcc, s13, v66
	v_lshl_add_u64 v[82:83], v[24:25], 0, v[64:65]
	s_nop 0
	v_addc_co_u32_e32 v87, vcc, 0, v67, vcc
	v_lshl_add_u64 v[84:85], v[66:67], 0, s[10:11]
	global_load_dwordx4 v[64:67], v[86:87], off
	global_load_dwordx4 v[68:71], v[84:85], off offset:48
	global_load_dwordx4 v[72:75], v[84:85], off offset:32
	global_load_dwordx4 v[76:79], v[84:85], off offset:16
	v_lshl_add_u64 v[26:27], v[24:25], 0, v[26:27]
	s_waitcnt vmcnt(0)
	v_mov_b64_e32 v[36:37], v[104:105]
	v_mov_b64_e32 v[38:39], v[106:107]
	v_mov_b64_e32 v[40:41], v[108:109]
	v_mov_b64_e32 v[42:43], v[110:111]
	v_mov_b64_e32 v[60:61], v[112:113]
	v_mov_b64_e32 v[62:63], v[114:115]
	v_mov_b64_e32 v[16:17], v[116:117]
	v_mov_b64_e32 v[18:19], v[118:119]
	v_mov_b64_e32 v[128:129], v[44:45]
	v_mov_b64_e32 v[130:131], v[46:47]
	v_mov_b64_e32 v[132:133], v[48:49]
	v_mov_b64_e32 v[134:135], v[50:51]
	v_mov_b64_e32 v[136:137], v[52:53]
	v_mov_b64_e32 v[138:139], v[54:55]
	v_mov_b64_e32 v[140:141], v[64:65]
	v_mov_b64_e32 v[142:143], v[66:67]
	v_mov_b64_e32 v[144:145], v[56:57]
	v_mov_b64_e32 v[146:147], v[58:59]
	v_mov_b64_e32 v[148:149], v[76:77]
	v_mov_b64_e32 v[150:151], v[78:79]
	v_mov_b64_e32 v[152:153], v[68:69]
	v_mov_b64_e32 v[154:155], v[70:71]
	v_mov_b64_e32 v[156:157], v[72:73]
	v_mov_b64_e32 v[158:159], v[74:75]
	v_and_b32_e32 v85, 0xffff0000, v36
	v_lshlrev_b32_e32 v84, 16, v36
	v_mul_f32_e32 v81, v85, v85
	v_lshlrev_b32_e32 v36, 16, v37
	v_fmac_f32_e32 v81, v84, v84
	v_and_b32_e32 v37, 0xffff0000, v37
	v_fmac_f32_e32 v81, v36, v36
	v_lshlrev_b32_e32 v86, 16, v38
	v_fmac_f32_e32 v81, v37, v37
	v_and_b32_e32 v87, 0xffff0000, v38
	v_fmac_f32_e32 v81, v86, v86
	v_lshlrev_b32_e32 v38, 16, v39
	v_fmac_f32_e32 v81, v87, v87
	v_and_b32_e32 v39, 0xffff0000, v39
	v_fmac_f32_e32 v81, v38, v38
	v_lshlrev_b32_e32 v88, 16, v40
	v_fmac_f32_e32 v81, v39, v39
	v_and_b32_e32 v89, 0xffff0000, v40
	v_fmac_f32_e32 v81, v88, v88
	v_lshlrev_b32_e32 v40, 16, v41
	v_fmac_f32_e32 v81, v89, v89
	v_and_b32_e32 v41, 0xffff0000, v41
	v_fmac_f32_e32 v81, v40, v40
	v_lshlrev_b32_e32 v90, 16, v42
	v_fmac_f32_e32 v81, v41, v41
	v_and_b32_e32 v91, 0xffff0000, v42
	v_and_b32_e32 v42, 0xffff0000, v43
	v_lshlrev_b32_e32 v43, 16, v43
	v_fmac_f32_e32 v81, v90, v90
	v_pk_mul_f32 v[92:93], v[42:43], v[42:43]
	v_fmac_f32_e32 v81, v91, v91
	v_add_f32_e32 v81, v93, v81
	v_add_f32_e32 v81, v92, v81
	ds_bpermute_b32 v92, v28, v81
	v_lshlrev_b32_e32 v94, 16, v61
	v_and_b32_e32 v95, 0xffff0000, v61
	v_lshlrev_b32_e32 v102, 16, v18
	v_and_b32_e32 v103, 0xffff0000, v18
	s_waitcnt lgkmcnt(0)
	v_add_f32_e32 v81, v81, v92
	ds_bpermute_b32 v93, v29, v81
	v_lshlrev_b32_e32 v92, 16, v60
	v_lshlrev_b32_e32 v96, 16, v62
	v_lshlrev_b32_e32 v98, 16, v63
	v_and_b32_e32 v99, 0xffff0000, v63
	s_waitcnt lgkmcnt(0)
	v_add_f32_e32 v81, v81, v93
	ds_bpermute_b32 v97, v30, v81
	v_and_b32_e32 v93, 0xffff0000, v60
	v_pk_add_f32 v[46:47], v[46:47], 1.0 op_sel_hi:[1,0]
	v_pk_add_f32 v[44:45], v[44:45], 1.0 op_sel_hi:[1,0]
	v_pk_add_f32 v[54:55], v[54:55], 1.0 op_sel_hi:[1,0]
	s_waitcnt lgkmcnt(0)
	v_add_f32_e32 v60, v81, v97
	ds_bpermute_b32 v61, v31, v60
	v_and_b32_e32 v97, 0xffff0000, v62
	v_pk_add_f32 v[52:53], v[52:53], 1.0 op_sel_hi:[1,0]
	v_pk_add_f32 v[50:51], v[50:51], 1.0 op_sel_hi:[1,0]
	v_pk_add_f32 v[48:49], v[48:49], 1.0 op_sel_hi:[1,0]
	s_waitcnt lgkmcnt(0)
	v_add_f32_e32 v60, v60, v61
	ds_bpermute_b32 v61, v32, v60
	v_pk_add_f32 v[58:59], v[58:59], 1.0 op_sel_hi:[1,0]
	v_pk_add_f32 v[56:57], v[56:57], 1.0 op_sel_hi:[1,0]
	v_mul_f32_e32 v81, v93, v93
	v_fmac_f32_e32 v81, v92, v92
	s_waitcnt lgkmcnt(0)
	v_add_f32_e32 v60, v60, v61
	ds_bpermute_b32 v61, v33, v60
	v_fmac_f32_e32 v81, v94, v94
	v_fmac_f32_e32 v81, v95, v95
	v_fmac_f32_e32 v81, v96, v96
	v_fmac_f32_e32 v81, v97, v97
	s_waitcnt lgkmcnt(0)
	v_add_f32_e32 v18, v60, v61
	v_fmamk_f32 v18, v18, 0x3a800000, v34
	v_rsq_f32_e32 v18, v18
	v_fmac_f32_e32 v81, v98, v98
	v_lshlrev_b32_e32 v100, 16, v16
	v_fmac_f32_e32 v81, v99, v99
	v_pk_mul_f32 v[36:37], v[36:37], v[18:19] op_sel_hi:[1,0]
	v_pk_mul_f32 v[60:61], v[84:85], v[18:19] op_sel_hi:[1,0]
	v_pk_mul_f32 v[38:39], v[38:39], v[18:19] op_sel_hi:[1,0]
	v_pk_mul_f32 v[62:63], v[86:87], v[18:19] op_sel_hi:[1,0]
	v_pk_mul_f32 v[40:41], v[40:41], v[18:19] op_sel_hi:[1,0]
	v_pk_mul_f32 v[84:85], v[88:89], v[18:19] op_sel_hi:[1,0]
	v_pk_mul_f32 v[42:43], v[42:43], v[18:19] op_sel:[1,0] op_sel_hi:[0,0]
	v_pk_mul_f32 v[86:87], v[90:91], v[18:19] op_sel_hi:[1,0]
	v_pk_mul_f32 v[60:61], v[12:13], v[60:61]
	v_pk_mul_f32 v[36:37], v[14:15], v[36:37]
	v_pk_mul_f32 v[62:63], v[8:9], v[62:63]
	v_pk_mul_f32 v[38:39], v[10:11], v[38:39]
	v_pk_mul_f32 v[84:85], v[4:5], v[84:85]
	v_pk_mul_f32 v[40:41], v[6:7], v[40:41]
	v_pk_mul_f32 v[86:87], v[0:1], v[86:87]
	v_pk_mul_f32 v[42:43], v[2:3], v[42:43]
	v_pk_fma_f32 v[46:47], v[46:47], v[36:37], v[66:67]
	v_pk_fma_f32 v[36:37], v[44:45], v[60:61], v[64:65]
	v_pk_fma_f32 v[44:45], v[54:55], v[38:39], v[78:79]
	v_pk_fma_f32 v[38:39], v[52:53], v[62:63], v[76:77]
	v_pk_fma_f32 v[50:51], v[50:51], v[40:41], v[74:75]
	v_pk_fma_f32 v[40:41], v[48:49], v[84:85], v[72:73]
	v_pk_fma_f32 v[48:49], v[58:59], v[42:43], v[70:71]
	v_pk_fma_f32 v[42:43], v[56:57], v[86:87], v[68:69]
	v_cvt_pk_bf16_f32 v36, v36, v37
	v_cvt_pk_bf16_f32 v37, v46, v47
	v_cvt_pk_bf16_f32 v38, v38, v39
	v_cvt_pk_bf16_f32 v39, v44, v45
	v_ashrrev_i32_e32 v18, 12, v80
	v_cvt_pk_bf16_f32 v40, v40, v41
	v_cvt_pk_bf16_f32 v41, v50, v51
	v_cvt_pk_bf16_f32 v42, v42, v43
	v_cvt_pk_bf16_f32 v43, v48, v49
	global_store_dwordx4 v[82:83], v[36:39], off
	global_store_dwordx4 v[82:83], v[40:43], off offset:16
	v_and_b32_e32 v101, 0xffff0000, v16
	v_mul_hi_i32_i24_e32 v37, 0x6000, v18
	v_mul_i32_i24_e32 v36, 0x6000, v18
	v_lshl_add_u64 v[36:37], s[66:67], 0, v[36:37]
	v_lshl_add_u64 v[48:49], v[36:37], 0, v[20:21]
	v_add_co_u32_e32 v50, vcc, s12, v48
	v_lshl_add_u64 v[68:69], v[48:49], 0, s[8:9]
	s_nop 0
	v_addc_co_u32_e32 v51, vcc, 0, v49, vcc
	v_cmp_eq_u32_e32 vcc, v160, v18
	s_cbranch_vccz .Lp6_reload
; __device__ __forceinline__ unsigned pk2(float lo, float hi) { f32x2 v = {lo, hi}; bf16x2_t b = __builtin_convertvector(v, bf16x2_t); return __builtin_bit_cast(unsigned, b); }
; __device__ __forceinline__ float bf_lo(unsigned u) { return __uint_as_float(u << 16); }
; __device__ __forceinline__ float bf_hi(unsigned u) { return __uint_as_float(u & 0xffff0000u); }
; __device__ __forceinline__ void norm_rows_bf(const bf16_t* __restrict__ X, const float* __restrict__ g, const float* __restrict__ mod, int sh_off, int sc_off, bf16_t* __restrict__ H, int G) {
;     ...
;         for (int q = 0; q < 2; ++q) { const int row = (row0 + q * NGW < MTOK) ? row0 + q * NGW : row0; const int b = row >> 12;
;             float v[16];
; #pragma unroll
;             for (int e = 0; e < 2; ++e) { v[8 * e] = bf_lo(w[q][e].x); v[8 * e + 1] = bf_hi(w[q][e].x); v[8 * e + 2] = bf_lo(w[q][e].y); v[8 * e + 3] = bf_hi(w[q][e].y);
;                 v[8 * e + 4] = bf_lo(w[q][e].z); v[8 * e + 5] = bf_hi(w[q][e].z); v[8 * e + 6] = bf_lo(w[q][e].w); v[8 * e + 7] = bf_hi(w[q][e].w); }
; #pragma unroll
;             for (int i = 0; i < 16; ++i) ss[q] += v[i] * v[i];
;             const float rn = __builtin_amdgcn_rsqf(wave_sum(ss[q]) * (1.0f / DM) + EPS);
;             const float* mb = mod + (size_t)b * NMOD; const int c = 16 * lane;
;             unsigned o[8];
; #pragma unroll
;             for (int j = 0; j < 4; ++j) { const f32x4 gv = *(const f32x4*)(g + c + 4 * j), sc = *(const f32x4*)(mb + sc_off + c + 4 * j), sh = *(const f32x4*)(mb + sh_off + c + 4 * j);
;                 const f32x4 x = (f32x4){v[4 * j], v[4 * j + 1], v[4 * j + 2], v[4 * j + 3]};
;                 const f32x4 y = x * rn * gv * (sc + 1.0f) + sh; o[2 * j] = pk2(y[0], y[1]); o[2 * j + 1] = pk2(y[2], y[3]); }
;             u32x4* op = (u32x4*)(H + (size_t)row * DM + c);
;             op[0] = (u32x4){o[0], o[1], o[2], o[3]}; op[1] = (u32x4){o[4], o[5], o[6], o[7]}; }
	v_mov_b64_e32 v[36:37], v[128:129]
	v_mov_b64_e32 v[38:39], v[130:131]
	v_mov_b64_e32 v[40:41], v[132:133]
	v_mov_b64_e32 v[42:43], v[134:135]
	v_mov_b64_e32 v[44:45], v[136:137]
	v_mov_b64_e32 v[46:47], v[138:139]
	v_mov_b64_e32 v[48:49], v[140:141]
	v_mov_b64_e32 v[50:51], v[142:143]
	v_mov_b64_e32 v[52:53], v[144:145]
	v_mov_b64_e32 v[54:55], v[146:147]
	v_mov_b64_e32 v[56:57], v[148:149]
	v_mov_b64_e32 v[58:59], v[150:151]
	v_mov_b64_e32 v[60:61], v[152:153]
	v_mov_b64_e32 v[62:63], v[154:155]
	v_mov_b64_e32 v[64:65], v[156:157]
	v_mov_b64_e32 v[66:67], v[158:159]
	s_branch .Lp6_join
.Lp6_reload:
	global_load_dwordx4 v[36:39], v[50:51], off
	global_load_dwordx4 v[40:43], v[68:69], off offset:32
	global_load_dwordx4 v[44:47], v[68:69], off offset:16
	v_add_co_u32_e32 v72, vcc, s13, v48
	v_lshl_add_u64 v[70:71], v[48:49], 0, s[10:11]
	s_nop 0
	v_addc_co_u32_e32 v73, vcc, 0, v49, vcc
	global_load_dwordx4 v[48:51], v[72:73], off
	global_load_dwordx4 v[52:55], v[68:69], off offset:48
	global_load_dwordx4 v[56:59], v[70:71], off offset:16
	global_load_dwordx4 v[60:63], v[70:71], off offset:48
	global_load_dwordx4 v[64:67], v[70:71], off offset:32
.Lp6_join:
	v_add_u32_e32 v120, s3, v35
	v_min_i32_e32 v120, s14, v120
	v_mov_b32_e32 v121, 0
	v_add_u32_e32 v122, s3, v120
	v_mov_b32_e32 v123, 0
	v_cmp_gt_i32_e32 vcc, s2, v122
	v_lshlrev_b64 v[124:125], 11, v[120:121]
	v_lshl_add_u64 v[126:127], v[22:23], 0, v[124:125]
	v_cndmask_b32_e32 v122, v120, v122, vcc
	global_load_dwordx4 v[104:107], v[126:127], off
	global_load_dwordx4 v[108:111], v[126:127], off offset:16
	v_lshlrev_b64 v[124:125], 11, v[122:123]
	v_lshl_add_u64 v[126:127], v[22:23], 0, v[124:125]
	global_load_dwordx4 v[112:115], v[126:127], off
	global_load_dwordx4 v[116:119], v[126:127], off offset:16
	v_fmac_f32_e32 v81, v100, v100
	v_lshlrev_b32_e32 v16, 16, v17
	v_fmac_f32_e32 v81, v101, v101
	v_and_b32_e32 v17, 0xffff0000, v17
	v_fmac_f32_e32 v81, v16, v16
	v_fmac_f32_e32 v81, v17, v17
	v_fmac_f32_e32 v81, v102, v102
	v_and_b32_e32 v18, 0xffff0000, v19
	v_lshlrev_b32_e32 v19, 16, v19
	v_fmac_f32_e32 v81, v103, v103
	v_pk_mul_f32 v[68:69], v[18:19], v[18:19]
	s_waitcnt vmcnt(11)
	v_pk_add_f32 v[36:37], v[36:37], 1.0 op_sel_hi:[1,0]
	v_add_f32_e32 v69, v69, v81
	v_add_f32_e32 v68, v68, v69
	ds_bpermute_b32 v69, v28, v68
	s_waitcnt vmcnt(9)
	v_pk_add_f32 v[44:45], v[44:45], 1.0 op_sel_hi:[1,0]
	v_pk_add_f32 v[42:43], v[42:43], 1.0 op_sel_hi:[1,0]
	v_pk_add_f32 v[40:41], v[40:41], 1.0 op_sel_hi:[1,0]
	s_waitcnt lgkmcnt(0)
	v_add_f32_e32 v68, v68, v69
	ds_bpermute_b32 v69, v29, v68
	s_waitcnt lgkmcnt(0)
	v_add_f32_e32 v68, v68, v69
	ds_bpermute_b32 v69, v30, v68
	s_waitcnt lgkmcnt(0)
	v_add_f32_e32 v68, v68, v69
	ds_bpermute_b32 v69, v31, v68
	s_waitcnt lgkmcnt(0)
	v_add_f32_e32 v68, v68, v69
	ds_bpermute_b32 v69, v32, v68
	s_waitcnt lgkmcnt(0)
	v_add_f32_e32 v68, v68, v69
	ds_bpermute_b32 v69, v33, v68
	s_waitcnt lgkmcnt(0)
	v_add_f32_e32 v68, v68, v69
	v_fmamk_f32 v68, v68, 0x3a800000, v34
	v_rsq_f32_e32 v68, v68
	s_nop 0
	v_pk_mul_f32 v[70:71], v[94:95], v[68:69] op_sel_hi:[1,0]
	v_pk_mul_f32 v[72:73], v[92:93], v[68:69] op_sel_hi:[1,0]
	v_pk_mul_f32 v[74:75], v[98:99], v[68:69] op_sel_hi:[1,0]
	v_pk_mul_f32 v[76:77], v[96:97], v[68:69] op_sel_hi:[1,0]
	v_pk_mul_f32 v[78:79], v[100:101], v[68:69] op_sel_hi:[1,0]
	v_pk_mul_f32 v[80:81], v[18:19], v[68:69] op_sel:[1,0] op_sel_hi:[0,0]
	v_pk_mul_f32 v[18:19], v[102:103], v[68:69] op_sel_hi:[1,0]
	v_pk_mul_f32 v[16:17], v[16:17], v[68:69] op_sel_hi:[1,0]
	v_pk_mul_f32 v[68:69], v[12:13], v[72:73]
	v_pk_mul_f32 v[70:71], v[14:15], v[70:71]
	v_pk_mul_f32 v[72:73], v[8:9], v[76:77]
	v_pk_mul_f32 v[74:75], v[10:11], v[74:75]
	v_pk_mul_f32 v[76:77], v[4:5], v[78:79]
	v_pk_mul_f32 v[78:79], v[0:1], v[18:19]
	v_pk_add_f32 v[18:19], v[38:39], 1.0 op_sel_hi:[1,0]
	v_pk_add_f32 v[38:39], v[46:47], 1.0 op_sel_hi:[1,0]
	v_pk_mul_f32 v[16:17], v[6:7], v[16:17]
	s_waitcnt vmcnt(8)
	v_pk_fma_f32 v[18:19], v[18:19], v[70:71], v[50:51]
	v_pk_fma_f32 v[36:37], v[36:37], v[68:69], v[48:49]
	s_waitcnt vmcnt(6)
	v_pk_fma_f32 v[38:39], v[38:39], v[74:75], v[58:59]
	v_pk_fma_f32 v[44:45], v[44:45], v[72:73], v[56:57]
	s_waitcnt vmcnt(4)
	v_pk_fma_f32 v[42:43], v[42:43], v[16:17], v[66:67]
	v_pk_fma_f32 v[40:41], v[40:41], v[76:77], v[64:65]
	v_cvt_pk_bf16_f32 v16, v36, v37
	v_cvt_pk_bf16_f32 v17, v18, v19
	v_cvt_pk_bf16_f32 v18, v44, v45
	v_cvt_pk_bf16_f32 v19, v38, v39
	v_cvt_pk_bf16_f32 v36, v40, v41
	v_cvt_pk_bf16_f32 v37, v42, v43
	v_pk_mul_f32 v[38:39], v[2:3], v[80:81]
	v_pk_add_f32 v[40:41], v[54:55], 1.0 op_sel_hi:[1,0]
	v_pk_add_f32 v[42:43], v[52:53], 1.0 op_sel_hi:[1,0]
	global_store_dwordx4 v[26:27], v[16:19], off
	v_pk_fma_f32 v[40:41], v[40:41], v[38:39], v[62:63]
	v_pk_fma_f32 v[38:39], v[42:43], v[78:79], v[60:61]
	v_add_u32_e32 v16, s3, v35
	v_cmp_lt_i32_e32 vcc, s14, v16
	v_cvt_pk_bf16_f32 v38, v38, v39
	v_cvt_pk_bf16_f32 v39, v40, v41
	s_or_b64 s[6:7], vcc, s[6:7]
	global_store_dwordx4 v[26:27], v[36:39], off offset:16
	s_andn2_b64 exec, exec, s[6:7]
	s_cbranch_execnz .LBB0_617
